# P3 L2 row warm-up two ticket rounds ahead (row t-256 instead of t-128)
# baseline (speedup 1.0000x reference)
; DI size_t sc_rowoff(int b, int t) { const int c = t >> 6; return (size_t)b * SC_PB + (size_t)4096 * (c * (c + 1) / 2) + (size_t)(t & 63) * (64 * (c + 1)); }
; DI void select_row(const float* SC, unsigned* dmask, int b, int t, int lane) {
;     unsigned* dm = dmask + ((size_t)b * SEQ + t) * 64;
;     const int nvalid = t + 1;
;     if (nvalid <= 256) {
;         const int w = lane;
;         const int lo = 32 * w; unsigned bits = 0u;
;         if (lo + 31 <= t) bits = 0xffffffffu; else if (lo <= t) bits = (2u << (t - lo)) - 1u;
;         dm[w] = bits; return;
;     }
;     const int nch = (nvalid + 255) >> 8;
;     const float* srow = SC + sc_rowoff(b, t) + 4 * lane;
.Lsel_pf_done:
	s_mov_b32 s99, 0x80000000
	v_mov_b32_e32 v121, v43
	v_lshl_add_u64 v[10:11], s[8:9], 0, v[120:121]
	s_cmpk_lt_u32 s65, 0x200
	s_cbranch_scc1 .Lsel_l2pf_skip
	s_add_i32 s8, s65, 0xffffff00
	s_lshr_b32 s9, s8, 6
	s_add_i32 s10, s9, 1
	s_mul_i32 s9, s9, s10
	s_lshl_b32 s9, s9, 13
	s_and_b32 s8, s8, 63
	s_mul_i32 s8, s8, s10
	s_lshl_b32 s8, s8, 8
	s_add_i32 s8, s8, s9
	s_and_b32 s14, s92, 8
	s_and_b32 s98, s47, 7
	s_or_b32 s14, s14, s98
	s_mul_i32 s14, s14, 0x840000
	s_add_i32 s8, s8, s14
	s_add_u32 s8, s44, s8
	s_addc_u32 s9, s45, 0
	s_lshl_b32 s10, s10, 1
	s_lshl_b64 s[10:11], 1, s10
	s_add_u32 s10, s10, -1
	s_addc_u32 s11, s11, -1
	v_lshlrev_b32_e32 v189, 3, v120
	s_mov_b32 m0, 0x1000
	s_mov_b64 vcc, exec
	s_mov_b64 exec, s[10:11]
	s_nop 1
	global_load_lds_dword v189, s[8:9]
	s_mov_b64 exec, vcc
